# retention QK/PV LDS reads with 14-deep lookahead ring (counted lgkmcnt)
# baseline (speedup 1.0000x reference)
.LBB0_863:
	s_mul_i32 s4, s49, 0x8800
	v_add_u32_e32 v8, s4, v173
	v_cvt_pk_bf16_f32 v6, v174, v175
	v_cvt_pk_bf16_f32 v7, v176, v177
	s_nop 1
	ds_read_b64_tr_b16 v[138:139], v8
	ds_read_b64_tr_b16 v[140:141], v8 offset:8704
	ds_read_b64_tr_b16 v[142:143], v8 offset:32
	ds_read_b64_tr_b16 v[144:145], v8 offset:8736
	ds_read_b64_tr_b16 v[146:147], v8 offset:64
	ds_read_b64_tr_b16 v[148:149], v8 offset:8768
	ds_read_b64_tr_b16 v[150:151], v8 offset:96
	ds_read_b64_tr_b16 v[152:153], v8 offset:8800
	ds_read_b64_tr_b16 v[198:199], v8 offset:128
	ds_read_b64_tr_b16 v[200:201], v8 offset:8832
	ds_read_b64_tr_b16 v[202:203], v8 offset:160
	ds_read_b64_tr_b16 v[204:205], v8 offset:8864
	ds_read_b64_tr_b16 v[206:207], v8 offset:192
	ds_read_b64_tr_b16 v[208:209], v8 offset:8896
	s_waitcnt lgkmcnt(12)
	v_mfma_f32_16x16x32_bf16 v[70:73], v[138:141], v[0:3], v[70:73]
	ds_read_b64_tr_b16 v[138:139], v8 offset:224
	ds_read_b64_tr_b16 v[140:141], v8 offset:8928
	s_waitcnt lgkmcnt(12)
	v_mfma_f32_16x16x32_bf16 v[66:69], v[142:145], v[0:3], v[66:69]
	ds_read_b64_tr_b16 v[142:143], v8 offset:256
	ds_read_b64_tr_b16 v[144:145], v8 offset:8960
	s_waitcnt lgkmcnt(12)
	v_mfma_f32_16x16x32_bf16 v[62:65], v[146:149], v[0:3], v[62:65]
	ds_read_b64_tr_b16 v[146:147], v8 offset:288
	ds_read_b64_tr_b16 v[148:149], v8 offset:8992
	s_waitcnt lgkmcnt(12)
	v_mfma_f32_16x16x32_bf16 v[58:61], v[150:153], v[0:3], v[58:61]
	ds_read_b64_tr_b16 v[150:151], v8 offset:320
	ds_read_b64_tr_b16 v[152:153], v8 offset:9024
	s_waitcnt lgkmcnt(12)
	v_mfma_f32_16x16x32_bf16 v[54:57], v[198:201], v[0:3], v[54:57]
	ds_read_b64_tr_b16 v[198:199], v8 offset:352
	ds_read_b64_tr_b16 v[200:201], v8 offset:9056
	s_waitcnt lgkmcnt(12)
	v_mfma_f32_16x16x32_bf16 v[50:53], v[202:205], v[0:3], v[50:53]
	ds_read_b64_tr_b16 v[202:203], v8 offset:384
	ds_read_b64_tr_b16 v[204:205], v8 offset:9088
	s_waitcnt lgkmcnt(12)
	v_mfma_f32_16x16x32_bf16 v[46:49], v[206:209], v[0:3], v[46:49]
	ds_read_b64_tr_b16 v[206:207], v8 offset:416
	ds_read_b64_tr_b16 v[208:209], v8 offset:9120
	s_waitcnt lgkmcnt(12)
	v_mfma_f32_16x16x32_bf16 v[42:45], v[138:141], v[0:3], v[42:45]
	ds_read_b64_tr_b16 v[138:139], v8 offset:448
	ds_read_b64_tr_b16 v[140:141], v8 offset:9152
	s_waitcnt lgkmcnt(12)
	v_mfma_f32_16x16x32_bf16 v[38:41], v[142:145], v[0:3], v[38:41]
	ds_read_b64_tr_b16 v[142:143], v8 offset:480
	ds_read_b64_tr_b16 v[144:145], v8 offset:9184
	s_waitcnt lgkmcnt(12)
	v_mfma_f32_16x16x32_bf16 v[34:37], v[146:149], v[0:3], v[34:37]
	ds_read_b64_tr_b16 v[146:147], v8 offset:17408
	ds_read_b64_tr_b16 v[148:149], v8 offset:26112
	s_waitcnt lgkmcnt(12)
	v_mfma_f32_16x16x32_bf16 v[30:33], v[150:153], v[0:3], v[30:33]
	ds_read_b64_tr_b16 v[150:151], v8 offset:17440
	ds_read_b64_tr_b16 v[152:153], v8 offset:26144
	s_waitcnt lgkmcnt(12)
	v_mfma_f32_16x16x32_bf16 v[26:29], v[198:201], v[0:3], v[26:29]
	ds_read_b64_tr_b16 v[198:199], v8 offset:17472
	ds_read_b64_tr_b16 v[200:201], v8 offset:26176
	s_waitcnt lgkmcnt(12)
	v_mfma_f32_16x16x32_bf16 v[22:25], v[202:205], v[0:3], v[22:25]
	ds_read_b64_tr_b16 v[202:203], v8 offset:17504
	ds_read_b64_tr_b16 v[204:205], v8 offset:26208
	s_waitcnt lgkmcnt(12)
	v_mfma_f32_16x16x32_bf16 v[18:21], v[206:209], v[0:3], v[18:21]
	ds_read_b64_tr_b16 v[206:207], v8 offset:17536
	ds_read_b64_tr_b16 v[208:209], v8 offset:26240
	s_waitcnt lgkmcnt(12)
	v_mfma_f32_16x16x32_bf16 v[14:17], v[138:141], v[0:3], v[14:17]
	ds_read_b64_tr_b16 v[138:139], v8 offset:17568
	ds_read_b64_tr_b16 v[140:141], v8 offset:26272
	s_waitcnt lgkmcnt(12)
	v_mfma_f32_16x16x32_bf16 v[10:13], v[142:145], v[0:3], v[10:13]
	ds_read_b64_tr_b16 v[142:143], v8 offset:17600
	ds_read_b64_tr_b16 v[144:145], v8 offset:26304
	s_waitcnt lgkmcnt(12)
	v_mfma_f32_16x16x32_bf16 v[70:73], v[146:149], v[4:7], v[70:73]
	ds_read_b64_tr_b16 v[146:147], v8 offset:17632
	ds_read_b64_tr_b16 v[148:149], v8 offset:26336
	s_waitcnt lgkmcnt(12)
	v_mfma_f32_16x16x32_bf16 v[66:69], v[150:153], v[4:7], v[66:69]
	ds_read_b64_tr_b16 v[150:151], v8 offset:17664
	ds_read_b64_tr_b16 v[152:153], v8 offset:26368
	s_waitcnt lgkmcnt(12)
	v_mfma_f32_16x16x32_bf16 v[62:65], v[198:201], v[4:7], v[62:65]
	ds_read_b64_tr_b16 v[198:199], v8 offset:17696
	ds_read_b64_tr_b16 v[200:201], v8 offset:26400
	s_waitcnt lgkmcnt(12)
	v_mfma_f32_16x16x32_bf16 v[58:61], v[202:205], v[4:7], v[58:61]
	ds_read_b64_tr_b16 v[202:203], v8 offset:17728
	ds_read_b64_tr_b16 v[204:205], v8 offset:26432
	s_waitcnt lgkmcnt(12)
	v_mfma_f32_16x16x32_bf16 v[54:57], v[206:209], v[4:7], v[54:57]
	ds_read_b64_tr_b16 v[206:207], v8 offset:17760
	ds_read_b64_tr_b16 v[208:209], v8 offset:26464
	s_waitcnt lgkmcnt(12)
	v_mfma_f32_16x16x32_bf16 v[50:53], v[138:141], v[4:7], v[50:53]
	ds_read_b64_tr_b16 v[138:139], v8 offset:17792
	ds_read_b64_tr_b16 v[140:141], v8 offset:26496
	s_waitcnt lgkmcnt(12)
	v_mfma_f32_16x16x32_bf16 v[46:49], v[142:145], v[4:7], v[46:49]
	ds_read_b64_tr_b16 v[142:143], v8 offset:17824
	ds_read_b64_tr_b16 v[144:145], v8 offset:26528
	s_waitcnt lgkmcnt(12)
	v_mfma_f32_16x16x32_bf16 v[42:45], v[146:149], v[4:7], v[42:45]
	ds_read_b64_tr_b16 v[146:147], v8 offset:17856
	ds_read_b64_tr_b16 v[148:149], v8 offset:26560
	s_waitcnt lgkmcnt(12)
	v_mfma_f32_16x16x32_bf16 v[38:41], v[150:153], v[4:7], v[38:41]
	ds_read_b64_tr_b16 v[150:151], v8 offset:17888
	ds_read_b64_tr_b16 v[152:153], v8 offset:26592
	s_waitcnt lgkmcnt(12)
	v_mfma_f32_16x16x32_bf16 v[34:37], v[198:201], v[4:7], v[34:37]
	s_waitcnt lgkmcnt(10)
	v_mfma_f32_16x16x32_bf16 v[30:33], v[202:205], v[4:7], v[30:33]
	s_waitcnt lgkmcnt(8)
	v_mfma_f32_16x16x32_bf16 v[26:29], v[206:209], v[4:7], v[26:29]
	s_waitcnt lgkmcnt(6)
	v_mfma_f32_16x16x32_bf16 v[22:25], v[138:141], v[4:7], v[22:25]
	s_waitcnt lgkmcnt(4)
	v_mfma_f32_16x16x32_bf16 v[18:21], v[142:145], v[4:7], v[18:21]
	s_waitcnt lgkmcnt(2)
	v_mfma_f32_16x16x32_bf16 v[14:17], v[146:149], v[4:7], v[14:17]
	s_waitcnt lgkmcnt(0)
	v_mfma_f32_16x16x32_bf16 v[10:13], v[150:153], v[4:7], v[10:13]

.LBB0_865:
	v_mov_b32_e32 v6, v170
	s_and_b32 s49, s48, 1
	v_lshlrev_b32_e32 v0, 4, v6
	v_and_b32_e32 v8, 0x1f0, v0
	v_lshrrev_b32_e32 v2, 5, v6
	v_add_u32_e32 v4, 0x200, v6
	v_lshl_add_u64 v[0:1], s[24:25], 0, v[8:9]
	v_add3_u32 v8, s45, v2, 64
	v_lshrrev_b32_e32 v4, 5, v4
	v_lshlrev_b64 v[2:3], 14, v[8:9]
	v_add3_u32 v8, s45, v4, 64
	v_lshl_add_u64 v[2:3], v[0:1], 0, v[2:3]
	v_lshlrev_b64 v[4:5], 14, v[8:9]
	v_lshl_add_u64 v[4:5], v[0:1], 0, v[4:5]
	global_load_dwordx4 v[110:113], v[2:3], off
	global_load_dwordx4 v[106:109], v[4:5], off
	v_add_u32_e32 v2, 0x400, v6
	v_lshrrev_b32_e32 v2, 5, v2
	v_add_u32_e32 v4, 0x600, v6
	v_add3_u32 v8, s45, v2, 64
	v_lshrrev_b32_e32 v4, 5, v4
	v_lshlrev_b64 v[2:3], 14, v[8:9]
	v_add3_u32 v8, s45, v4, 64
	v_lshlrev_b64 v[4:5], 14, v[8:9]
	v_lshl_add_u64 v[2:3], v[0:1], 0, v[2:3]
	v_lshl_add_u64 v[0:1], v[0:1], 0, v[4:5]
	v_mov_b32_e32 v6, v170
	global_load_dwordx4 v[118:121], v[2:3], off
	global_load_dwordx4 v[114:117], v[0:1], off
	s_cmp_gt_i32 s45, s16
	v_lshlrev_b32_e32 v0, 4, v6
	v_and_b32_e32 v8, 0x1f0, v0
	v_lshrrev_b32_e32 v2, 5, v6
	v_add_u32_e32 v4, 0x200, v6
	v_lshl_add_u64 v[0:1], s[26:27], 0, v[8:9]
	v_add3_u32 v8, s45, v2, 64
	v_lshrrev_b32_e32 v4, 5, v4
	v_lshlrev_b64 v[2:3], 14, v[8:9]
	v_add3_u32 v8, s45, v4, 64
	v_lshl_add_u64 v[2:3], v[0:1], 0, v[2:3]
	v_lshlrev_b64 v[4:5], 14, v[8:9]
	v_lshl_add_u64 v[4:5], v[0:1], 0, v[4:5]
	global_load_dwordx4 v[126:129], v[2:3], off
	global_load_dwordx4 v[122:125], v[4:5], off
	v_add_u32_e32 v2, 0x400, v6
	v_lshrrev_b32_e32 v2, 5, v2
	v_add_u32_e32 v4, 0x600, v6
	v_add3_u32 v8, s45, v2, 64
	v_lshrrev_b32_e32 v4, 5, v4
	v_lshlrev_b64 v[2:3], 14, v[8:9]
	v_add3_u32 v8, s45, v4, 64
	v_lshl_add_u64 v[2:3], v[0:1], 0, v[2:3]
	v_lshlrev_b64 v[4:5], 14, v[8:9]
	v_lshl_add_u64 v[0:1], v[0:1], 0, v[4:5]
	global_load_dwordx4 v[134:137], v[2:3], off
	global_load_dwordx4 v[130:133], v[0:1], off
	s_cbranch_scc1 .LBB0_864
	s_mul_i32 s4, s49, 0x8400
	v_add_u32_e32 v8, s4, v195
	ds_read_b128 v[0:3], v8
	ds_read_b128 v[4:7], v8 offset:8448
	ds_read_b128 v[174:177], v8 offset:16896
	ds_read_b128 v[198:201], v8 offset:25344
	ds_read_b128 v[202:205], v8 offset:64
	ds_read_b128 v[206:209], v8 offset:8512
	ds_read_b128 v[210:213], v8 offset:16960
	ds_read_b128 v[214:217], v8 offset:25408
	ds_read_b128 v[218:221], v8 offset:128
	ds_read_b128 v[226:229], v8 offset:8576
	ds_read_b128 v[230:233], v8 offset:17024
	ds_read_b128 v[234:237], v8 offset:25472
	ds_read_b128 v[238:241], v8 offset:192
	ds_read_b128 v[242:245], v8 offset:8640
	s_add_i32 s4, s45, 63
	s_cmp_le_u32 s4, s9
	s_waitcnt lgkmcnt(13)
	v_mfma_f32_16x16x32_bf16 v[150:153], v[0:3], v[102:105], 0
	ds_read_b128 v[0:3], v8 offset:17088
	s_waitcnt lgkmcnt(13)
	v_mfma_f32_16x16x32_bf16 v[146:149], v[4:7], v[102:105], 0
	ds_read_b128 v[4:7], v8 offset:25536
	s_waitcnt lgkmcnt(13)
	v_mfma_f32_16x16x32_bf16 v[142:145], v[174:177], v[102:105], 0
	ds_read_b128 v[174:177], v8 offset:256
	s_waitcnt lgkmcnt(13)
	v_mfma_f32_16x16x32_bf16 v[138:141], v[198:201], v[102:105], 0
	ds_read_b128 v[198:201], v8 offset:8704
	s_waitcnt lgkmcnt(13)
	v_mfma_f32_16x16x32_bf16 v[150:153], v[202:205], v[98:101], v[150:153]
	ds_read_b128 v[202:205], v8 offset:17152
	s_waitcnt lgkmcnt(13)
	v_mfma_f32_16x16x32_bf16 v[146:149], v[206:209], v[98:101], v[146:149]
	ds_read_b128 v[206:209], v8 offset:25600
	s_waitcnt lgkmcnt(13)
	v_mfma_f32_16x16x32_bf16 v[142:145], v[210:213], v[98:101], v[142:145]
	ds_read_b128 v[210:213], v8 offset:320
	s_waitcnt lgkmcnt(13)
	v_mfma_f32_16x16x32_bf16 v[138:141], v[214:217], v[98:101], v[138:141]
	ds_read_b128 v[214:217], v8 offset:8768
	s_waitcnt lgkmcnt(13)
	v_mfma_f32_16x16x32_bf16 v[150:153], v[218:221], v[94:97], v[150:153]
	ds_read_b128 v[218:221], v8 offset:17216
	s_waitcnt lgkmcnt(13)
	v_mfma_f32_16x16x32_bf16 v[146:149], v[226:229], v[94:97], v[146:149]
	ds_read_b128 v[226:229], v8 offset:25664
	s_waitcnt lgkmcnt(13)
	v_mfma_f32_16x16x32_bf16 v[142:145], v[230:233], v[94:97], v[142:145]
	ds_read_b128 v[230:233], v8 offset:384
	s_waitcnt lgkmcnt(13)
	v_mfma_f32_16x16x32_bf16 v[138:141], v[234:237], v[94:97], v[138:141]
	ds_read_b128 v[234:237], v8 offset:8832
	s_waitcnt lgkmcnt(13)
	v_mfma_f32_16x16x32_bf16 v[150:153], v[238:241], v[90:93], v[150:153]
	ds_read_b128 v[238:241], v8 offset:17280
	s_waitcnt lgkmcnt(13)
	v_mfma_f32_16x16x32_bf16 v[146:149], v[242:245], v[90:93], v[146:149]
	ds_read_b128 v[242:245], v8 offset:25728
	s_waitcnt lgkmcnt(13)
	v_mfma_f32_16x16x32_bf16 v[142:145], v[0:3], v[90:93], v[142:145]
	ds_read_b128 v[0:3], v8 offset:448
	s_waitcnt lgkmcnt(13)
	v_mfma_f32_16x16x32_bf16 v[138:141], v[4:7], v[90:93], v[138:141]
	ds_read_b128 v[4:7], v8 offset:8896
	s_waitcnt lgkmcnt(13)
	v_mfma_f32_16x16x32_bf16 v[150:153], v[174:177], v[86:89], v[150:153]
	ds_read_b128 v[174:177], v8 offset:17344
	s_waitcnt lgkmcnt(13)
	v_mfma_f32_16x16x32_bf16 v[146:149], v[198:201], v[86:89], v[146:149]
	ds_read_b128 v[198:201], v8 offset:25792
	s_waitcnt lgkmcnt(13)
	v_mfma_f32_16x16x32_bf16 v[142:145], v[202:205], v[86:89], v[142:145]
	s_waitcnt lgkmcnt(12)
	v_mfma_f32_16x16x32_bf16 v[138:141], v[206:209], v[86:89], v[138:141]
	s_waitcnt lgkmcnt(11)
	v_mfma_f32_16x16x32_bf16 v[150:153], v[210:213], v[82:85], v[150:153]
	s_waitcnt lgkmcnt(10)
	v_mfma_f32_16x16x32_bf16 v[146:149], v[214:217], v[82:85], v[146:149]
	s_waitcnt lgkmcnt(9)
	v_mfma_f32_16x16x32_bf16 v[142:145], v[218:221], v[82:85], v[142:145]
	s_waitcnt lgkmcnt(8)
	v_mfma_f32_16x16x32_bf16 v[138:141], v[226:229], v[82:85], v[138:141]
	s_waitcnt lgkmcnt(7)
	v_mfma_f32_16x16x32_bf16 v[150:153], v[230:233], v[78:81], v[150:153]
	s_waitcnt lgkmcnt(6)
	v_mfma_f32_16x16x32_bf16 v[146:149], v[234:237], v[78:81], v[146:149]
	s_waitcnt lgkmcnt(5)
	v_mfma_f32_16x16x32_bf16 v[142:145], v[238:241], v[78:81], v[142:145]
	s_waitcnt lgkmcnt(4)
	v_mfma_f32_16x16x32_bf16 v[138:141], v[242:245], v[78:81], v[138:141]
	s_waitcnt lgkmcnt(3)
	v_mfma_f32_16x16x32_bf16 v[150:153], v[0:3], v[74:77], v[150:153]
	s_waitcnt lgkmcnt(2)
	v_mfma_f32_16x16x32_bf16 v[146:149], v[4:7], v[74:77], v[146:149]
	s_waitcnt lgkmcnt(1)
	v_mfma_f32_16x16x32_bf16 v[142:145], v[174:177], v[74:77], v[142:145]
	s_waitcnt lgkmcnt(0)
	v_mfma_f32_16x16x32_bf16 v[138:141], v[198:201], v[74:77], v[138:141]
	s_mov_b64 s[4:5], -1
	s_cbranch_scc0 .LBB0_868
	v_cvt_f32_i32_e32 v0, v196
	s_mov_b64 s[4:5], 0
	v_mul_f32_e32 v0, v178, v0
	v_exp_f32_e32 v8, v0
	s_nop 0
	v_mul_f32_e32 v0, s40, v8
	v_pk_mul_f32 v[2:3], s[40:41], v[0:1] op_sel_hi:[1,0]
	v_pk_mul_f32 v[0:1], s[42:43], v[0:1] op_sel_hi:[1,0]
	v_pk_mul_f32 v[2:3], v[2:3], v[150:151]
	v_pk_mul_f32 v[4:5], v[0:1], v[152:153]
	v_cvt_pk_bf16_f32 v0, v2, v3
	v_mul_f32_e32 v2, s44, v8
	v_cvt_pk_bf16_f32 v1, v4, v5
	v_pk_mul_f32 v[4:5], s[40:41], v[2:3] op_sel_hi:[1,0]
	v_pk_mul_f32 v[2:3], s[42:43], v[2:3] op_sel_hi:[1,0]
	v_pk_mul_f32 v[4:5], v[4:5], v[146:147]
	v_pk_mul_f32 v[6:7], v[2:3], v[148:149]
	v_cvt_pk_bf16_f32 v2, v4, v5
	v_mul_f32_e32 v4, s37, v8
	v_cvt_pk_bf16_f32 v3, v6, v7
	v_pk_mul_f32 v[6:7], s[40:41], v[4:5] op_sel_hi:[1,0]
	v_pk_mul_f32 v[4:5], s[42:43], v[4:5] op_sel_hi:[1,0]
	v_pk_mul_f32 v[6:7], v[6:7], v[142:143]
	v_pk_mul_f32 v[154:155], v[4:5], v[144:145]
	v_cvt_pk_bf16_f32 v4, v6, v7
	v_mul_f32_e32 v6, s36, v8
	v_cvt_pk_bf16_f32 v5, v154, v155
	v_pk_mul_f32 v[154:155], s[40:41], v[6:7] op_sel_hi:[1,0]
	v_pk_mul_f32 v[6:7], s[42:43], v[6:7] op_sel_hi:[1,0]
	v_pk_mul_f32 v[174:175], v[154:155], v[138:139]
	v_pk_mul_f32 v[176:177], v[6:7], v[140:141]
